# attention QK: all K-fragment LDS reads of a tile issued up front, each MFMA waits only for its own fragment (counted lgkmcnt), NSA t1 fragments in v64-79
# speedup vs baseline: 1.0030x; 1.0030x over previous
; #define LAS __attribute__((address_space(3)))
; DI f32x16 mfma32(bf16x8 a, bf16x8 b, f32x16 c) { return __builtin_amdgcn_mfma_f32_32x32x16_bf16(a, b, c, 0, 0, 0); }
; DI f32x16 zero16() { f32x16 z; for (int i = 0; i < 16; ++i) z[i] = 0.f; return z; }
; template <int NKS>
; DI void qk_tile(const LAS unsigned char* kt, int kstride, const bf16x8 (&qf)[NKS], f32x16 (&s)[2], int r, int hh, const bf16x8 rf) {
;     const bf16x8 of = ones_frag(hh);
; #pragma unroll
;     for (int t = 0; t < 2; ++t) {
;         bf16x8 kf[NKS];
; #pragma unroll
;         for (int ks = 0; ks < NKS; ++ks) kf[ks] = *(const LAS bf16x8*)(kt + (32 * t + r) * kstride + 32 * ks + 16 * hh);
;         __builtin_amdgcn_sched_barrier(0);
;         s[t] = zero16();
; #pragma unroll
;         for (int ks = 0; ks < NKS; ++ks) s[t] = mfma32(kf[ks], qf[ks], s[t]);
;         s[t] = mfma32(of, rf, s[t]);
;     }
; DI void nsa_attn_phase(int wv, LAS unsigned char* lds, const bf16_t* Q, const bf16_t* slab, const bf16_t* VT2, const float* gates, const bf16_t* KCMP, const bf16_t* VCMPT,
;                        const float* rel_bias, bf16_t* O) {
;     ...
;                 auto process = [&](const LAS unsigned char* kb, int j) {
;                     const int k0 = 64 * j;
;                     const bool selbit = (br == 0) ? (((mysel >> j) & 1u) != 0u) : true;
;                     if (br == 0 && __ballot(selbit) == 0ull) return;
;                     const bool far = (TW - (k0 + 63) >= 127) && (br == 0 || (TW + 31 - k0 < 512));
;                     f32x16 s[2];
;                     qk_tile<4>(kb, KS, qf, s, r, hh, ref_frag(-m, far ? (selbit ? c31 : NEGF) : 0.f, hh));
;                     if (!far) {
;                         const int d0 = tq - k0 - 4 * hh;
; #pragma unroll
;                         for (int t = 0; t < 2; ++t)
; #pragma unroll
;                             for (int i = 0; i < 16; ++i) {
;                                 const int dist = d0 - (32 * t + (i & 3) + 8 * (i >> 2));
;                                 const float bias = mylut[dist < 0 ? 0 : (dist > 127 ? 127 : dist)];
;                                 const bool valid = selbit && dist >= 0 && (br == 0 || dist < 512);
;                                 s[t][i] = valid ? s[t][i] + bias : NEGF;
;                             }
.LBB0_2427:
	s_andn2_b64 vcc, exec, s[6:7]
	s_cbranch_vccnz .LBB0_2420
	s_mulk_i32 s0, 0x4600
	s_add_i32 s0, s0, 0
	v_add3_u32 v7, s0, v212, v241
	ds_read_b128 v[8:11], v7 offset:35328
	ds_read_b128 v[12:15], v7 offset:35360
	ds_read_b128 v[64:67], v7 offset:35392
	ds_read_b128 v[68:71], v7 offset:35424
	ds_read_b128 v[72:75], v7 offset:39936
	ds_read_b128 v[76:79], v7 offset:39968
	ds_read_b128 v[250:253], v7 offset:40000
	ds_read_b128 v[224:227], v7 offset:40032
	v_cvt_pk_bf16_f32 v3, -v4, s0
	v_perm_b32 v3, 0, v3, v229
	v_lshlrev_b32_e32 v2, 16, v3
	v_sub_f32_e64 v2, -v4, v2
	v_cvt_pk_bf16_f32 v2, v2, s0
	v_mul_i32_i24_e32 v0, 0xffffffc0, v144
	v_lshl_or_b32 v3, v2, 16, v3
	v_add_u32_e32 v2, s92, v0
	s_movk_i32 s1, 0x7e
	v_cmp_lt_i32_e64 s[6:7], s1, v2
	v_add_u32_e32 v2, s93, v0
	v_cmp_gt_i32_e32 vcc, s83, v2
	s_or_b64 s[30:31], s[8:9], vcc
	s_or_b64 vcc, s[26:27], s[4:5]
	v_mov_b32_e32 v2, 0xfffff14a
	v_cndmask_b32_e32 v2, v2, v240, vcc
	s_and_b64 s[4:5], s[6:7], s[30:31]
	v_cndmask_b32_e64 v2, 0, v2, s[4:5]
	v_mov_b32_e32 v208, 0x1100
	v_perm_b32 v2, 0, v2, v229
	s_xor_b64 s[4:5], s[4:5], -1
	v_cndmask_b32_e64 v246, 0, v3, s[2:3]
	v_cndmask_b32_e64 v247, 0, v2, s[2:3]
	v_mov_b32_e32 v248, v1
	v_mov_b32_e32 v249, v1
	s_waitcnt lgkmcnt(7)
	v_mfma_f32_32x32x16_bf16 v[160:175], v[8:11], v[176:179], 0
	s_waitcnt lgkmcnt(6)
	v_mfma_f32_32x32x16_bf16 v[160:175], v[12:15], v[180:183], v[160:175]
	s_waitcnt lgkmcnt(5)
	v_mfma_f32_32x32x16_bf16 v[160:175], v[64:67], v[184:187], v[160:175]
	s_waitcnt lgkmcnt(4)
	v_mfma_f32_32x32x16_bf16 v[160:175], v[68:71], v[188:191], v[160:175]
	v_mfma_f32_32x32x16_bf16 v[160:175], v[192:195], v[246:249], v[160:175]
	s_waitcnt lgkmcnt(3)
	v_mfma_f32_32x32x16_bf16 v[144:159], v[72:75], v[176:179], 0
	s_waitcnt lgkmcnt(2)
	v_mfma_f32_32x32x16_bf16 v[144:159], v[76:79], v[180:183], v[144:159]
	s_waitcnt lgkmcnt(1)
	v_mfma_f32_32x32x16_bf16 v[144:159], v[250:253], v[184:187], v[144:159]
	s_waitcnt lgkmcnt(0)
	v_mfma_f32_32x32x16_bf16 v[144:159], v[224:227], v[188:191], v[144:159]
	v_mfma_f32_32x32x16_bf16 v[144:159], v[192:195], v[246:249], v[144:159]
	s_and_saveexec_b64 s[6:7], s[4:5]
	s_cbranch_execz .LBB0_2430
	v_add_u32_e32 v2, v0, v210
	v_sub_u32_e32 v2, v2, v233
	v_add_u32_e32 v2, 64, v2
	v_mov_b32_e32 v3, 63
	v_cndmask_b32_e32 v2, v3, v2, vcc
	v_lshl_add_u32 v2, v2, 2, s70
	ds_read2_b32 v[20:21], v2 offset0:59 offset1:58
	ds_read2_b32 v[22:23], v2 offset0:57 offset1:56
	ds_read2_b32 v[24:25], v2 offset0:51 offset1:50
	ds_read2_b32 v[26:27], v2 offset0:49 offset1:48
	ds_read2_b32 v[28:29], v2 offset0:43 offset1:42
	ds_read2_b32 v[30:31], v2 offset0:41 offset1:40
	ds_read2_b32 v[32:33], v2 offset0:35 offset1:34
	ds_read2_b32 v[34:35], v2 offset0:33 offset1:32
	ds_read2_b32 v[36:37], v2 offset0:27 offset1:26
	ds_read2_b32 v[38:39], v2 offset0:25 offset1:24
	ds_read2_b32 v[40:41], v2 offset0:19 offset1:18
	ds_read2_b32 v[42:43], v2 offset0:17 offset1:16
	ds_read2_b32 v[44:45], v2 offset0:11 offset1:10
	ds_read2_b32 v[46:47], v2 offset0:9 offset1:8
	ds_read2_b32 v[48:49], v2 offset0:3 offset1:2
	ds_read2_b32 v[50:51], v2 offset0:1 offset1:0
	s_waitcnt lgkmcnt(15)
	v_add_f32_e32 v160, v160, v20
	v_add_f32_e32 v161, v161, v21
	s_waitcnt lgkmcnt(14)
	v_add_f32_e32 v162, v162, v22
	v_add_f32_e32 v163, v163, v23
	s_waitcnt lgkmcnt(13)
	v_add_f32_e32 v164, v164, v24
	v_add_f32_e32 v165, v165, v25
	s_waitcnt lgkmcnt(12)
	v_add_f32_e32 v166, v166, v26
	v_add_f32_e32 v167, v167, v27
	s_waitcnt lgkmcnt(11)
	v_add_f32_e32 v168, v168, v28
	v_add_f32_e32 v169, v169, v29
	s_waitcnt lgkmcnt(10)
	v_add_f32_e32 v170, v170, v30
	v_add_f32_e32 v171, v171, v31
	s_waitcnt lgkmcnt(9)
	v_add_f32_e32 v172, v172, v32
	v_add_f32_e32 v173, v173, v33
	s_waitcnt lgkmcnt(8)
	v_add_f32_e32 v174, v174, v34
	v_add_f32_e32 v175, v175, v35
	s_waitcnt lgkmcnt(7)
	v_add_f32_e32 v144, v144, v36
	v_add_f32_e32 v145, v145, v37
	s_waitcnt lgkmcnt(6)
	v_add_f32_e32 v146, v146, v38
	v_add_f32_e32 v147, v147, v39
	s_waitcnt lgkmcnt(5)
	v_add_f32_e32 v148, v148, v40
	v_add_f32_e32 v149, v149, v41
	s_waitcnt lgkmcnt(4)
	v_add_f32_e32 v150, v150, v42
	v_add_f32_e32 v151, v151, v43
	s_waitcnt lgkmcnt(3)
	v_add_f32_e32 v152, v152, v44
	v_add_f32_e32 v153, v153, v45
	s_waitcnt lgkmcnt(2)
	v_add_f32_e32 v154, v154, v46
	v_add_f32_e32 v155, v155, v47
	s_waitcnt lgkmcnt(1)
	v_add_f32_e32 v156, v156, v48
	v_add_f32_e32 v157, v157, v49
	s_waitcnt lgkmcnt(0)
	v_add_f32_e32 v158, v158, v50
	v_add_f32_e32 v159, v159, v51

; DI float fexp2(float x) { return __builtin_amdgcn_exp2f(x); }
; DI f32x16 mfma32(bf16x8 a, bf16x8 b, f32x16 c) { return __builtin_amdgcn_mfma_f32_32x32x16_bf16(a, b, c, 0, 0, 0); }
; DI void softmax_lazy1(f32x16& s, float& m, float& l, f32x16 (&o)[2], int hh) {
;     float mx = s[0];
; #pragma unroll
;     for (int i = 1; i < 16; ++i) mx = fmaxf(mx, s[i]);
;     mx = fmaxf(mx, __shfl_xor(mx, 32));
;     const bool live = mx > -1e29f;
;     const bool slow = live && (mx > 32.f || (mx < -32.f && l == 0.f));
;     if (__ballot(slow) != 0ull) {
;         const float shift = (live && (mx > 0.f || l == 0.f)) ? mx : 0.f;
;         const float alpha = (l == 0.f) ? 0.f : fexp2(-shift);
;         s = mfma32(ones_frag(hh), ref_frag(-shift, 0.f, hh), s);
;         l *= alpha; m += shift;
;         o[0] *= alpha; o[1] *= alpha;
;     }
.LBB0_2828:
	v_lshl_or_b32 v0, s48, 5, v194
	v_mad_u32_u24 v0, v0, s80, v206
	ds_read_b128 v[68:71], v0
	ds_read_b128 v[212:215], v0 offset:32
	ds_read_b128 v[216:219], v0 offset:64
	ds_read_b128 v[234:237], v0 offset:96
	ds_read_b128 v[238:241], v0 offset:128
	ds_read_b128 v[242:245], v0 offset:160
		s_waitcnt lgkmcnt(5)
	v_mfma_f32_32x32x16_bf16 v[84:99], v[68:71], v[100:103], 0
	v_cvt_pk_bf16_f32 v0, -v199, s0
	v_perm_b32 v0, 0, v0, v229
	v_lshlrev_b32_e32 v2, 16, v0
	v_sub_f32_e64 v2, -v199, v2
	v_cvt_pk_bf16_f32 v2, v2, s0
	v_lshl_or_b32 v0, v2, 16, v0
	v_cndmask_b32_e64 v0, 0, v0, s[2:3]
	s_waitcnt lgkmcnt(4)
	v_mfma_f32_32x32x16_bf16 v[84:99], v[212:215], v[104:107], v[84:99]
	v_mov_b32_e32 v2, v1
	v_mov_b32_e32 v3, v1
	v_cvt_pk_bf16_f32 v211, -v201, s0
	v_perm_b32 v211, 0, v211, v229
	s_mov_b64 s[6:7], 0
	s_waitcnt lgkmcnt(3)
	v_mfma_f32_32x32x16_bf16 v[84:99], v[216:219], v[116:119], v[84:99]
	v_mfma_f32_32x32x16_bf16 v[68:83], v[68:71], v[108:111], 0
	s_waitcnt lgkmcnt(2)
	v_mfma_f32_32x32x16_bf16 v[84:99], v[234:237], v[120:123], v[84:99]
	v_mfma_f32_32x32x16_bf16 v[68:83], v[212:215], v[112:115], v[68:83]
	s_waitcnt lgkmcnt(1)
	v_mfma_f32_32x32x16_bf16 v[84:99], v[238:241], v[132:135], v[84:99]
	v_mfma_f32_32x32x16_bf16 v[68:83], v[216:219], v[124:127], v[68:83]
	s_waitcnt lgkmcnt(0)
	v_mfma_f32_32x32x16_bf16 v[84:99], v[242:245], v[136:139], v[84:99]
	v_mfma_f32_32x32x16_bf16 v[68:83], v[234:237], v[128:131], v[68:83]
	v_mfma_f32_32x32x16_bf16 v[84:99], v[172:175], v[0:3], v[84:99]
	v_lshlrev_b32_e32 v0, 16, v211
	v_sub_f32_e64 v0, -v201, v0
	v_cvt_pk_bf16_f32 v0, v0, s0
	v_lshl_or_b32 v0, v0, 16, v211
	v_cndmask_b32_e64 v0, 0, v0, s[2:3]
	s_nop 6
	v_max_f32_e32 v2, v85, v85
	v_mfma_f32_32x32x16_bf16 v[68:83], v[238:241], v[140:143], v[68:83]
	v_max_f32_e32 v3, v84, v84
	v_max_f32_e32 v2, v3, v2
	v_max3_f32 v2, v2, v86, v87
	v_max3_f32 v2, v2, v88, v89
	v_max3_f32 v2, v2, v90, v91
	v_max3_f32 v2, v2, v92, v93
	v_max3_f32 v2, v2, v94, v95
	v_mfma_f32_32x32x16_bf16 v[68:83], v[242:245], v[144:147], v[68:83]
	v_max3_f32 v2, v2, v96, v97
	v_max3_f32 v212, v2, v98, v99
	v_mov_b32_e32 v2, v1
	v_mov_b32_e32 v3, v1
	v_mov_b32_e32 v213, v212
	s_nop 0
	v_mfma_f32_32x32x16_bf16 v[68:83], v[172:175], v[0:3], v[68:83]
	v_permlane32_swap_b32_e32 v213, v212
	v_max_f32_e32 v211, v213, v213
	v_max_f32_e32 v211, v212, v211
	v_cmp_lt_f32_e64 s[4:5], s40, v211
	v_cmp_lt_f32_e64 s[6:7], s63, v211
	v_cmp_gt_f32_e64 s[26:27], s76, v211
	v_cmp_eq_f32_e32 vcc, 0, v200
	s_and_b64 s[26:27], s[26:27], vcc
	s_or_b64 s[6:7], s[6:7], s[26:27]
	s_and_b64 s[6:7], s[6:7], s[4:5]
	s_cmp_eq_u64 s[6:7], 0
	s_cbranch_scc1 .LBB0_2836
	v_cmp_lt_f32_e32 vcc, 0, v211
	v_cmp_eq_f32_e64 s[6:7], 0, v200
	s_or_b64 s[24:25], vcc, s[6:7]
	s_and_b64 vcc, s[4:5], s[24:25]
	v_cndmask_b32_e32 v211, 0, v211, vcc
	v_exp_f32_e64 v0, -v211
	v_cvt_pk_bf16_f32 v2, -v211, s0
	v_mov_b32_e32 v3, v1
	v_add_f32_e32 v199, v199, v211
	v_cndmask_b32_e64 v212, v0, 0, s[6:7]
	v_perm_b32 v0, 0, v2, v229
	v_lshlrev_b32_e32 v2, 16, v0
	v_sub_f32_e64 v2, -v211, v2
	v_cvt_pk_bf16_f32 v2, v2, s0
	v_lshl_or_b32 v0, v2, 16, v0
	v_cndmask_b32_e64 v0, 0, v0, s[2:3]
	v_mov_b32_e32 v2, v1
	v_mul_f32_e32 v200, v200, v212
	v_pk_mul_f32 v[34:35], v[34:35], v[212:213] op_sel_hi:[1,0]
	v_mfma_f32_32x32x16_bf16 v[84:99], v[172:175], v[0:3], v[84:99]
	v_mul_f32_e64 v32, v32, v212
	v_mul_f32_e64 v33, v33, v212
	v_mul_f32_e64 v30, v30, v212
	v_mul_f32_e64 v31, v31, v212
	v_mul_f32_e64 v28, v28, v212
	v_mul_f32_e64 v29, v29, v212
	v_pk_mul_f32 v[26:27], v[26:27], v[212:213] op_sel_hi:[1,0]
	v_pk_mul_f32 v[24:25], v[24:25], v[212:213] op_sel_hi:[1,0]
	v_pk_mul_f32 v[22:23], v[22:23], v[212:213] op_sel_hi:[1,0]
	v_pk_mul_f32 v[20:21], v[20:21], v[212:213] op_sel_hi:[1,0]
	v_pk_mul_f32 v[18:19], v[18:19], v[212:213] op_sel_hi:[1,0]
	v_pk_mul_f32 v[16:17], v[16:17], v[212:213] op_sel_hi:[1,0]
	v_pk_mul_f32 v[14:15], v[14:15], v[212:213] op_sel_hi:[1,0]
	v_pk_mul_f32 v[12:13], v[12:13], v[212:213] op_sel_hi:[1,0]
	v_pk_mul_f32 v[10:11], v[10:11], v[212:213] op_sel_hi:[1,0]
	v_pk_mul_f32 v[8:9], v[8:9], v[212:213] op_sel_hi:[1,0]
	v_pk_mul_f32 v[6:7], v[6:7], v[212:213] op_sel_hi:[1,0]
	v_pk_mul_f32 v[4:5], v[4:5], v[212:213] op_sel_hi:[1,0]

; #define LAS __attribute__((address_space(3)))
; DI float fexp2(float x) { return __builtin_amdgcn_exp2f(x); }
; DI f32x16 mfma32(bf16x8 a, bf16x8 b, f32x16 c) { return __builtin_amdgcn_mfma_f32_32x32x16_bf16(a, b, c, 0, 0, 0); }
; DI void softmax_lazy1(f32x16& s, float& m, float& l, f32x16 (&o)[2], int hh) {
;     float mx = s[0];
; #pragma unroll
;     for (int i = 1; i < 16; ++i) mx = fmaxf(mx, s[i]);
;     mx = fmaxf(mx, __shfl_xor(mx, 32));
;     const bool live = mx > -1e29f;
;     const bool slow = live && (mx > 32.f || (mx < -32.f && l == 0.f));
;     if (__ballot(slow) != 0ull) {
;         const float shift = (live && (mx > 0.f || l == 0.f)) ? mx : 0.f;
;         const float alpha = (l == 0.f) ? 0.f : fexp2(-shift);
;         s = mfma32(ones_frag(hh), ref_frag(-shift, 0.f, hh), s);
;         l *= alpha; m += shift;
;         o[0] *= alpha; o[1] *= alpha;
;     }
; DI void mla_qblock(int wv, int w, LAS unsigned char* lds, const bf16_t* Q, const bf16_t* KN, const bf16_t* KR, const bf16_t* VT, bf16_t* O, size_t tok0, int h, int qb) {
;     ...
;     int bi = 0;
;     for (int t = 0; t < nfull; ++t) {
;         const int bn = bi == 2 ? 0 : bi + 1;
;         MLA_LSTORE(bn);
;         if (t + 2 < nt) MLA_GLOAD(t + 2);
;         const LAS unsigned char* kb = lds + bi * TILE;
; #pragma nounroll
;         for (int tt = 0; tt < 2; ++tt) {
;             f32x16 s0, s1;
;             MLA_QK1(tt);
;             softmax_lazy1(s0, m0, l0, o0, hh); softmax_lazy1(s1, m1, l1, o1, hh);
;             pv_sub2(kb + VOFF, VS, 64 * tt, s0, s1, o0, o1, r, hh);
;         }
;         __syncthreads();
;         bi = bn;
;     }
; #pragma nounroll
;     for (int t = nfull; t < nt; ++t) {
;         const int bn = bi == 2 ? 0 : bi + 1;
;         if (t + 1 < nt) MLA_LSTORE(bn);
;         if (t + 2 < nt) MLA_GLOAD(t + 2);
;         const int k0 = 64 * t;
;         if (k0 <= R0 + 63) {
;             const LAS unsigned char* kb = lds + bi * TILE;
; #pragma nounroll
;             for (int tt = 0; tt < 2; ++tt) {
;                 f32x16 s0, s1;
;                 MLA_QK1(tt);
; #pragma unroll
;                 for (int i = 0; i < 16; ++i) { const int key = k0 + 32 * tt + crow(i, hh); if (key > tq0) s0[i] = NEGF; if (key > tq1) s1[i] = NEGF; }
;                 softmax_lazy1(s0, m0, l0, o0, hh); softmax_lazy1(s1, m1, l1, o1, hh);
.LBB0_2860:
	s_lshl_b32 s4, s46, 5
	v_or_b32_e32 v0, s4, v194
	v_mad_u32_u24 v0, v0, s80, v165
	ds_read_b128 v[84:87], v0
	ds_read_b128 v[170:173], v0 offset:32
	ds_read_b128 v[202:205], v0 offset:64
	ds_read_b128 v[210:213], v0 offset:96
	ds_read_b128 v[214:217], v0 offset:128
	ds_read_b128 v[218:221], v0 offset:160
		s_waitcnt lgkmcnt(5)
	v_mfma_f32_32x32x16_bf16 v[68:83], v[84:87], v[100:103], 0
	v_cvt_pk_bf16_f32 v0, -v199, s0
	v_perm_b32 v0, 0, v0, v229
	v_lshlrev_b32_e32 v2, 16, v0
	v_sub_f32_e64 v2, -v199, v2
	v_cvt_pk_bf16_f32 v2, v2, s0
	v_lshl_or_b32 v0, v2, 16, v0
	v_cndmask_b32_e64 v0, 0, v0, s[2:3]
	s_waitcnt lgkmcnt(4)
	v_mfma_f32_32x32x16_bf16 v[68:83], v[170:173], v[104:107], v[68:83]
	v_mov_b32_e32 v2, v1
	v_mov_b32_e32 v3, v1
	v_or_b32_e32 v169, s4, v168
	v_cmp_le_i32_e32 vcc, v169, v178
	v_or_b32_e32 v174, 10, v169
	v_or_b32_e32 v175, 11, v169
	v_cmp_lt_i32_e64 s[4:5], v169, v178
	v_mfma_f32_32x32x16_bf16 v[84:99], v[84:87], v[108:111], 0
	v_or_b32_e32 v206, 24, v169
	s_mov_b64 s[24:25], 0
	s_waitcnt lgkmcnt(3)
	v_mfma_f32_32x32x16_bf16 v[68:83], v[202:205], v[116:119], v[68:83]
	v_mfma_f32_32x32x16_bf16 v[84:99], v[170:173], v[112:115], v[84:99]
	v_or_b32_e32 v170, 2, v169
	v_or_b32_e32 v171, 3, v169
	v_or_b32_e32 v172, 8, v169
	v_or_b32_e32 v173, 9, v169
	s_waitcnt lgkmcnt(2)
	v_mfma_f32_32x32x16_bf16 v[68:83], v[210:213], v[120:123], v[68:83]
	v_mfma_f32_32x32x16_bf16 v[84:99], v[202:205], v[124:127], v[84:99]
	v_or_b32_e32 v202, 16, v169
	v_or_b32_e32 v203, 17, v169
	v_or_b32_e32 v204, 18, v169
	v_or_b32_e32 v205, 19, v169
	s_waitcnt lgkmcnt(1)
	v_mfma_f32_32x32x16_bf16 v[68:83], v[214:217], v[132:135], v[68:83]
	v_mfma_f32_32x32x16_bf16 v[84:99], v[210:213], v[128:131], v[84:99]
	v_or_b32_e32 v210, 25, v169
	v_or_b32_e32 v211, 26, v169
	v_or_b32_e32 v212, 27, v169
	s_waitcnt lgkmcnt(0)
	v_mfma_f32_32x32x16_bf16 v[68:83], v[218:221], v[136:139], v[68:83]
	v_mfma_f32_32x32x16_bf16 v[84:99], v[214:217], v[140:143], v[84:99]
	v_mfma_f32_32x32x16_bf16 v[68:83], v[160:163], v[0:3], v[68:83]
	v_cvt_pk_bf16_f32 v0, -v201, s0
	v_perm_b32 v0, 0, v0, v229
	v_lshlrev_b32_e32 v2, 16, v0
	v_sub_f32_e64 v2, -v201, v2
	v_cvt_pk_bf16_f32 v2, v2, s0
	v_lshl_or_b32 v0, v2, 16, v0
	v_cndmask_b32_e64 v0, 0, v0, s[2:3]
	v_mfma_f32_32x32x16_bf16 v[84:99], v[218:221], v[144:147], v[84:99]
	s_nop 3
	v_cndmask_b32_e32 v68, v231, v68, vcc
	v_cmp_le_i32_e32 vcc, v170, v178
	v_mov_b32_e32 v2, v1
	v_cndmask_b32_e64 v69, v231, v69, s[4:5]
	v_cndmask_b32_e32 v70, v231, v70, vcc
	v_cmp_le_i32_e32 vcc, v171, v178
	v_mfma_f32_32x32x16_bf16 v[84:99], v[160:163], v[0:3], v[84:99]
	s_nop 0
	v_cndmask_b32_e32 v71, v231, v71, vcc
	v_cmp_le_i32_e32 vcc, v172, v178
	v_max_f32_e32 v0, v69, v69
	v_max_f32_e32 v2, v68, v68
	v_cndmask_b32_e32 v72, v231, v72, vcc
	v_cmp_le_i32_e32 vcc, v173, v178
	v_max_f32_e32 v0, v2, v0
	v_max3_f32 v0, v0, v70, v71
	v_cndmask_b32_e32 v73, v231, v73, vcc
	v_cmp_le_i32_e32 vcc, v174, v178
	v_max3_f32 v0, v0, v72, v73
	s_nop 0
	v_cndmask_b32_e32 v74, v231, v74, vcc
	v_cmp_le_i32_e32 vcc, v175, v178
	s_nop 1
	v_cndmask_b32_e32 v75, v231, v75, vcc
	v_cmp_le_i32_e32 vcc, v202, v178
	v_max3_f32 v0, v0, v74, v75
	s_nop 0
	v_cndmask_b32_e32 v76, v231, v76, vcc
	v_cmp_le_i32_e32 vcc, v203, v178
	s_nop 1
	v_cndmask_b32_e32 v77, v231, v77, vcc
	v_cmp_le_i32_e32 vcc, v204, v178
	v_max3_f32 v0, v0, v76, v77
	s_nop 0
	v_cndmask_b32_e32 v78, v231, v78, vcc
	v_cmp_le_i32_e32 vcc, v205, v178
	s_nop 1
	v_cndmask_b32_e32 v79, v231, v79, vcc
	v_cmp_le_i32_e32 vcc, v206, v178
	v_max3_f32 v0, v0, v78, v79
	s_nop 0
	v_cndmask_b32_e32 v80, v231, v80, vcc
	v_cmp_le_i32_e32 vcc, v210, v178
	s_nop 1
	v_cndmask_b32_e32 v81, v231, v81, vcc
	v_cmp_le_i32_e32 vcc, v211, v178
	v_max3_f32 v0, v0, v80, v81
	s_nop 0
	v_cndmask_b32_e32 v82, v231, v82, vcc
	v_cmp_le_i32_e32 vcc, v212, v178
	s_nop 1
	v_cndmask_b32_e32 v83, v231, v83, vcc
	v_max3_f32 v0, v0, v82, v83
	v_mov_b32_e32 v2, v0
	s_nop 1
	v_permlane32_swap_b32_e32 v2, v0
	v_max_f32_e32 v2, v2, v2
	v_max_f32_e32 v0, v0, v2
	v_cmp_lt_f32_e64 s[4:5], s40, v0
	v_cmp_lt_f32_e64 s[24:25], s63, v0
	v_cmp_gt_f32_e64 s[26:27], s76, v0
	v_cmp_eq_f32_e32 vcc, 0, v200
	s_and_b64 s[26:27], s[26:27], vcc
	s_or_b64 s[24:25], s[24:25], s[26:27]
	s_and_b64 s[24:25], s[24:25], s[4:5]
	s_cmp_eq_u64 s[24:25], 0
	s_cbranch_scc1 .LBB0_2868
	v_cmp_lt_f32_e32 vcc, 0, v0
	v_cmp_eq_f32_e64 s[6:7], 0, v200
	s_or_b64 s[24:25], vcc, s[6:7]
	s_and_b64 vcc, s[4:5], s[24:25]
	v_cndmask_b32_e32 v213, 0, v0, vcc
	v_exp_f32_e64 v0, -v213
	v_cvt_pk_bf16_f32 v2, -v213, s0
	v_mov_b32_e32 v3, v1
	v_add_f32_e32 v199, v199, v213
	v_cndmask_b32_e64 v214, v0, 0, s[6:7]
	v_perm_b32 v0, 0, v2, v229
	v_lshlrev_b32_e32 v2, 16, v0
	v_sub_f32_e64 v2, -v213, v2
	v_cvt_pk_bf16_f32 v2, v2, s0
	v_lshl_or_b32 v0, v2, 16, v0
	v_cndmask_b32_e64 v0, 0, v0, s[2:3]
	v_mov_b32_e32 v2, v1
	v_mul_f32_e32 v200, v200, v214
	v_pk_mul_f32 v[34:35], v[34:35], v[214:215] op_sel_hi:[1,0]
	v_mfma_f32_32x32x16_bf16 v[68:83], v[160:163], v[0:3], v[68:83]
	v_mul_f32_e64 v32, v32, v214
	v_mul_f32_e64 v33, v33, v214
	v_mul_f32_e64 v30, v30, v214
	v_mul_f32_e64 v31, v31, v214
	v_mul_f32_e64 v28, v28, v214
	v_mul_f32_e64 v29, v29, v214
	v_pk_mul_f32 v[26:27], v[26:27], v[214:215] op_sel_hi:[1,0]
	v_pk_mul_f32 v[24:25], v[24:25], v[214:215] op_sel_hi:[1,0]
	v_pk_mul_f32 v[22:23], v[22:23], v[214:215] op_sel_hi:[1,0]
	v_pk_mul_f32 v[20:21], v[20:21], v[214:215] op_sel_hi:[1,0]
	v_pk_mul_f32 v[18:19], v[18:19], v[214:215] op_sel_hi:[1,0]
	v_pk_mul_f32 v[16:17], v[16:17], v[214:215] op_sel_hi:[1,0]
	v_pk_mul_f32 v[14:15], v[14:15], v[214:215] op_sel_hi:[1,0]
	v_pk_mul_f32 v[12:13], v[12:13], v[214:215] op_sel_hi:[1,0]
	v_pk_mul_f32 v[10:11], v[10:11], v[214:215] op_sel_hi:[1,0]
	v_pk_mul_f32 v[8:9], v[8:9], v[214:215] op_sel_hi:[1,0]
	v_pk_mul_f32 v[6:7], v[6:7], v[214:215] op_sel_hi:[1,0]
	v_pk_mul_f32 v[4:5], v[4:5], v[214:215] op_sel_hi:[1,0]
